# FoX loop: K/V fragment ring reads issued after their consuming MFMA so the 12 v_mov_b64 register rotations per iteration disappear (on top of the half-iteration stagger)
# baseline (speedup 1.0000x reference)
.Lfx_lead_out:
	v_mfma_f32_32x32x16_bf16 v[18:33], v[158:161], v[122:125], v[18:33]
	ds_bpermute_b32 v1, v203, v206
	v_lshlrev_b64 v[36:37], 11, v[182:183]
	v_lshl_add_u64 v[36:37], v[178:179], 0, v[36:37]
	s_waitcnt lgkmcnt(0)
	v_add_f32_e32 v1, v206, v1
	v_rcp_f32_e32 v34, v1
	v_mfma_f32_32x32x16_bf16 v[2:17], v[142:145], v[122:125], v[2:17]
	v_mfma_f32_32x32x16_bf16 v[18:33], v[154:157], v[118:121], v[18:33]
	v_mfma_f32_32x32x16_bf16 v[2:17], v[138:141], v[118:121], v[2:17]
	v_mfma_f32_32x32x16_bf16 v[18:33], v[150:153], v[114:117], v[18:33]
	v_mfma_f32_32x32x16_bf16 v[2:17], v[134:137], v[114:117], v[2:17]
	v_mfma_f32_32x32x16_bf16 v[18:33], v[146:149], v[110:113], v[18:33]
	v_mfma_f32_32x32x16_bf16 v[2:17], v[130:133], v[110:113], v[2:17]
	s_nop 10
	v_mul_f32_e64 v18, v18, v34
	v_mul_f32_e64 v19, v19, v34
	v_mul_f32_e64 v20, v20, v34
	v_mul_f32_e64 v21, v21, v34
	v_cvt_pk_bf16_f32 v18, v18, v19
	v_cvt_pk_bf16_f32 v19, v20, v21
	global_store_dwordx2 v[36:37], v[18:19], off
	v_pk_mul_f32 v[18:19], v[22:23], v[34:35] op_sel_hi:[1,0]
	v_pk_mul_f32 v[20:21], v[24:25], v[34:35] op_sel_hi:[1,0]
	v_pk_mul_f32 v[2:3], v[2:3], v[34:35] op_sel_hi:[1,0]
	v_pk_mul_f32 v[4:5], v[4:5], v[34:35] op_sel_hi:[1,0]
	v_cvt_pk_bf16_f32 v2, v2, v3
	v_cvt_pk_bf16_f32 v3, v4, v5
	global_store_dwordx2 v[36:37], v[2:3], off offset:64
	v_pk_mul_f32 v[2:3], v[6:7], v[34:35] op_sel_hi:[1,0]
	v_pk_mul_f32 v[4:5], v[8:9], v[34:35] op_sel_hi:[1,0]
	v_cvt_pk_bf16_f32 v18, v18, v19
	v_cvt_pk_bf16_f32 v19, v20, v21
	v_cvt_pk_bf16_f32 v2, v2, v3
	v_cvt_pk_bf16_f32 v3, v4, v5
	global_store_dwordx2 v[36:37], v[18:19], off offset:16
	v_pk_mul_f32 v[18:19], v[26:27], v[34:35] op_sel_hi:[1,0]
	v_pk_mul_f32 v[20:21], v[28:29], v[34:35] op_sel_hi:[1,0]
	global_store_dwordx2 v[36:37], v[2:3], off offset:80
	v_pk_mul_f32 v[2:3], v[10:11], v[34:35] op_sel_hi:[1,0]
	v_pk_mul_f32 v[4:5], v[12:13], v[34:35] op_sel_hi:[1,0]
	v_cvt_pk_bf16_f32 v18, v18, v19
	v_cvt_pk_bf16_f32 v19, v20, v21
	v_cvt_pk_bf16_f32 v2, v2, v3
	v_cvt_pk_bf16_f32 v3, v4, v5
	global_store_dwordx2 v[36:37], v[18:19], off offset:32
	v_pk_mul_f32 v[18:19], v[30:31], v[34:35] op_sel_hi:[1,0]
	v_pk_mul_f32 v[20:21], v[32:33], v[34:35] op_sel_hi:[1,0]
	global_store_dwordx2 v[36:37], v[2:3], off offset:96
	v_pk_mul_f32 v[2:3], v[14:15], v[34:35] op_sel_hi:[1,0]
	v_pk_mul_f32 v[4:5], v[16:17], v[34:35] op_sel_hi:[1,0]
	v_cvt_pk_bf16_f32 v18, v18, v19
	v_cvt_pk_bf16_f32 v19, v20, v21
	v_cvt_pk_bf16_f32 v2, v2, v3
	v_cvt_pk_bf16_f32 v3, v4, v5
	global_store_dwordx2 v[36:37], v[18:19], off offset:48
	global_store_dwordx2 v[36:37], v[2:3], off offset:112
	s_setprio 0
	s_waitcnt lgkmcnt(0)
	s_barrier
	s_add_i32 s43, s43, 1
	s_cmp_eq_u32 s43, 8
	s_cbranch_scc1 .LBB0_164

.LBB0_183:
	ds_read_b128 v[34:37], v175
	ds_read_b128 v[38:41], v175 offset:16
	ds_read_b128 v[42:45], v175 offset:64
	ds_read_b128 v[46:49], v175 offset:80
	ds_read_b128 v[50:53], v175 offset:128
	ds_read_b128 v[54:57], v175 offset:144
	ds_read_b128 v[58:61], v175 offset:192
	ds_read_b128 v[62:65], v175 offset:208
	s_add_i32 s37, s49, 0x18000
	s_waitcnt lgkmcnt(4)
	v_mfma_f32_32x32x16_bf16 v[34:49], v[126:129], v[66:69], v[34:49]
	s_and_b32 s37, s37, 0xc000
	v_add_u32_e32 v1, s37, v189
	s_andn2_b64 vcc, exec, s[38:39]
	s_waitcnt lgkmcnt(0)
	v_mfma_f32_32x32x16_bf16 v[50:65], v[106:109], v[66:69], v[50:65]
	v_mfma_f32_32x32x16_bf16 v[34:49], v[98:101], v[70:73], v[34:49]
	v_mfma_f32_32x32x16_bf16 v[50:65], v[102:105], v[70:73], v[50:65]
	v_mfma_f32_32x32x16_bf16 v[34:49], v[86:89], v[74:77], v[34:49]
	ds_read_b128 v[126:129], v1 offset:32768
	ds_read_b128 v[98:101], v1 offset:33792
	ds_read_b128 v[86:89], v1 offset:34816
	v_mfma_f32_32x32x16_bf16 v[50:65], v[94:97], v[74:77], v[50:65]
	v_mfma_f32_32x32x16_bf16 v[34:49], v[82:85], v[78:81], v[34:49]
	ds_read_b128 v[82:85], v1 offset:35840
	ds_read_b128 v[106:109], v1 offset:40960
	ds_read_b128 v[102:105], v1 offset:41984
	ds_read_b128 v[94:97], v1 offset:43008
	v_mfma_f32_32x32x16_bf16 v[50:65], v[90:93], v[78:81], v[50:65]
	ds_read_b128 v[90:93], v1 offset:44032
	s_cbranch_vccnz .LBB0_185
	v_add_u32_e32 v1, s50, v166
	v_add_u32_e32 v163, 0xe0, v1
	v_add_u32_e32 v162, 0xc0, v1
	v_cmp_le_i32_e32 vcc, v163, v186
	s_nop 6
	v_cndmask_b32_e32 v50, v239, v50, vcc
	v_cmp_lt_i32_e32 vcc, v162, v186
	s_nop 1
	v_cndmask_b32_e32 v35, v239, v35, vcc
	v_cmp_le_i32_e32 vcc, v162, v186
	v_add_u32_e32 v162, 0xe1, v1
	s_nop 0
	v_cndmask_b32_e32 v34, v239, v34, vcc
	v_cmp_le_i32_e32 vcc, v162, v186
	v_add_u32_e32 v162, 0xc2, v1
	s_nop 0
	v_cndmask_b32_e32 v51, v239, v51, vcc
	v_cmp_le_i32_e32 vcc, v162, v186
	v_add_u32_e32 v162, 0xe2, v1
	s_nop 0
	v_cndmask_b32_e32 v36, v239, v36, vcc
	v_cmp_le_i32_e32 vcc, v162, v186
	v_add_u32_e32 v162, 0xc3, v1
	s_nop 0
	v_cndmask_b32_e32 v52, v239, v52, vcc
	v_cmp_le_i32_e32 vcc, v162, v186
	v_add_u32_e32 v162, 0xe3, v1
	s_nop 0
	v_cndmask_b32_e32 v37, v239, v37, vcc
	v_cmp_le_i32_e32 vcc, v162, v186
	v_add_u32_e32 v162, 0xc4, v1
	s_nop 0
	v_cndmask_b32_e32 v53, v239, v53, vcc
	v_cmp_le_i32_e32 vcc, v162, v186
	v_add_u32_e32 v162, 0xe4, v1
	s_nop 0
	v_cndmask_b32_e32 v38, v239, v38, vcc
	v_cmp_le_i32_e32 vcc, v162, v186
	v_add_u32_e32 v162, 0xc5, v1
	s_nop 0
	v_cndmask_b32_e32 v54, v239, v54, vcc
	v_cmp_le_i32_e32 vcc, v162, v186
	v_add_u32_e32 v162, 0xe5, v1
	s_nop 0
	v_cndmask_b32_e32 v39, v239, v39, vcc
	v_cmp_le_i32_e32 vcc, v162, v186
	v_add_u32_e32 v162, 0xc6, v1
	s_nop 0
	v_cndmask_b32_e32 v55, v239, v55, vcc
	v_cmp_le_i32_e32 vcc, v162, v186
	v_add_u32_e32 v162, 0xe6, v1
	s_nop 0
	v_cndmask_b32_e32 v40, v239, v40, vcc
	v_cmp_le_i32_e32 vcc, v162, v186
	v_add_u32_e32 v162, 0xc7, v1
	s_nop 0
	v_cndmask_b32_e32 v56, v239, v56, vcc
	v_cmp_le_i32_e32 vcc, v162, v186
	v_add_u32_e32 v162, 0xe7, v1
	s_nop 0
	v_cndmask_b32_e32 v41, v239, v41, vcc
	v_cmp_le_i32_e32 vcc, v162, v186
	v_add_u32_e32 v162, 0xd0, v1
	s_nop 0
	v_cndmask_b32_e32 v57, v239, v57, vcc
	v_cmp_le_i32_e32 vcc, v162, v186
	v_add_u32_e32 v162, 0xf0, v1
	s_nop 0
	v_cndmask_b32_e32 v42, v239, v42, vcc
	v_cmp_le_i32_e32 vcc, v162, v186
	v_add_u32_e32 v162, 0xd1, v1
	s_nop 0
	v_cndmask_b32_e32 v58, v239, v58, vcc
	v_cmp_le_i32_e32 vcc, v162, v186
	v_add_u32_e32 v162, 0xf1, v1
	s_nop 0
	v_cndmask_b32_e32 v43, v239, v43, vcc
	v_cmp_le_i32_e32 vcc, v162, v186
	v_add_u32_e32 v162, 0xd2, v1
	s_nop 0
	v_cndmask_b32_e32 v59, v239, v59, vcc
	v_cmp_le_i32_e32 vcc, v162, v186
	v_add_u32_e32 v162, 0xf2, v1
	s_nop 0
	v_cndmask_b32_e32 v44, v239, v44, vcc
	v_cmp_le_i32_e32 vcc, v162, v186
	v_add_u32_e32 v162, 0xd3, v1
	s_nop 0
	v_cndmask_b32_e32 v60, v239, v60, vcc
	v_cmp_le_i32_e32 vcc, v162, v186
	v_add_u32_e32 v162, 0xf3, v1
	s_nop 0
	v_cndmask_b32_e32 v45, v239, v45, vcc
	v_cmp_le_i32_e32 vcc, v162, v186
	v_add_u32_e32 v162, 0xd4, v1
	s_nop 0
	v_cndmask_b32_e32 v61, v239, v61, vcc
	v_cmp_le_i32_e32 vcc, v162, v186
	v_add_u32_e32 v162, 0xf4, v1
	s_nop 0
	v_cndmask_b32_e32 v46, v239, v46, vcc
	v_cmp_le_i32_e32 vcc, v162, v186
	v_add_u32_e32 v162, 0xd5, v1
	s_nop 0
	v_cndmask_b32_e32 v62, v239, v62, vcc
	v_cmp_le_i32_e32 vcc, v162, v186
	v_add_u32_e32 v162, 0xf5, v1
	s_nop 0
	v_cndmask_b32_e32 v47, v239, v47, vcc
	v_cmp_le_i32_e32 vcc, v162, v186
	v_add_u32_e32 v162, 0xd6, v1
	s_nop 0
	v_cndmask_b32_e32 v63, v239, v63, vcc
	v_cmp_le_i32_e32 vcc, v162, v186
	v_add_u32_e32 v162, 0xf6, v1
	s_nop 0
	v_cndmask_b32_e32 v48, v239, v48, vcc
	v_cmp_le_i32_e32 vcc, v162, v186
	v_add_u32_e32 v162, 0xd7, v1
	v_add_u32_e32 v1, 0xf7, v1
	v_cndmask_b32_e32 v64, v239, v64, vcc
	v_cmp_le_i32_e32 vcc, v162, v186
	s_nop 1
	v_cndmask_b32_e32 v49, v239, v49, vcc
	v_cmp_le_i32_e32 vcc, v1, v186
	s_nop 1
	v_cndmask_b32_e32 v65, v239, v65, vcc
.LBB0_185:
	v_mfma_f32_32x32x16_bf16 v[18:33], v[158:161], v[122:125], v[18:33]
	s_nop 4
	v_max3_f32 v1, v34, v35, v36
	v_max3_f32 v1, v1, v37, v38
	v_max3_f32 v1, v1, v39, v40
	v_max3_f32 v1, v1, v41, v42
	v_max3_f32 v1, v1, v43, v44
	v_max3_f32 v1, v1, v45, v46
	v_max3_f32 v1, v1, v47, v48
	v_mfma_f32_32x32x16_bf16 v[18:33], v[154:157], v[118:121], v[18:33]
	s_add_i32 s37, s49, 0xc000
	s_and_b32 s37, s37, 0xc000
	v_add_u32_e32 v194, s37, v189
	v_mfma_f32_32x32x16_bf16 v[2:17], v[142:145], v[122:125], v[2:17]
	ds_read_b128 v[158:161], v194 offset:36864
	ds_read_b128 v[154:157], v194 offset:37888
	ds_read_b128 v[142:145], v194 offset:38912
	v_mfma_f32_32x32x16_bf16 v[18:33], v[150:153], v[114:117], v[18:33]
	v_max_f32_e32 v150, v51, v51
	v_max_f32_e32 v151, v50, v50
	v_mfma_f32_32x32x16_bf16 v[2:17], v[138:141], v[118:121], v[2:17]
	ds_read_b128 v[138:141], v194 offset:39936
	v_mfma_f32_32x32x16_bf16 v[18:33], v[146:149], v[110:113], v[18:33]
	v_max_f32_e32 v146, v151, v150
	v_max3_f32 v146, v146, v52, v53
	v_max3_f32 v146, v146, v54, v55
	v_max3_f32 v146, v146, v56, v57
	v_max3_f32 v122, v146, v58, v59
	v_max3_f32 v122, v122, v60, v61
	v_max3_f32 v122, v122, v62, v63
	v_mfma_f32_32x32x16_bf16 v[2:17], v[134:137], v[114:117], v[2:17]
	v_max3_f32 v122, v122, v64, v65
	v_max3_f32 v1, v1, v49, v122
	ds_bpermute_b32 v118, v203, v1
	ds_read_b128 v[150:153], v194 offset:45056
	ds_read_b128 v[146:149], v194 offset:46080
	ds_read_b128 v[134:137], v194 offset:47104
	s_waitcnt lgkmcnt(3)
	v_max3_f32 v1, v207, v1, v118
	v_mfma_f32_32x32x16_bf16 v[2:17], v[130:133], v[110:113], v[2:17]
	ds_read_b128 v[130:133], v194 offset:48128
	v_sub_f32_e32 v114, v207, v1
	v_exp_f32_e32 v114, v114
	s_nop 0
	v_cmp_neq_f32_e32 vcc, 1.0, v114
	s_cbranch_vccz .LBB0_187
	v_pk_mul_f32 v[32:33], v[32:33], v[114:115] op_sel_hi:[1,0]
	v_pk_mul_f32 v[30:31], v[30:31], v[114:115] op_sel_hi:[1,0]
	v_pk_mul_f32 v[28:29], v[28:29], v[114:115] op_sel_hi:[1,0]
	v_pk_mul_f32 v[26:27], v[26:27], v[114:115] op_sel_hi:[1,0]
	v_pk_mul_f32 v[24:25], v[24:25], v[114:115] op_sel_hi:[1,0]
	v_pk_mul_f32 v[22:23], v[22:23], v[114:115] op_sel_hi:[1,0]
	v_pk_mul_f32 v[20:21], v[20:21], v[114:115] op_sel_hi:[1,0]
	v_pk_mul_f32 v[18:19], v[18:19], v[114:115] op_sel_hi:[1,0]
	v_pk_mul_f32 v[16:17], v[16:17], v[114:115] op_sel_hi:[1,0]
	v_pk_mul_f32 v[14:15], v[14:15], v[114:115] op_sel_hi:[1,0]
	v_pk_mul_f32 v[12:13], v[12:13], v[114:115] op_sel_hi:[1,0]
	v_pk_mul_f32 v[10:11], v[10:11], v[114:115] op_sel_hi:[1,0]
	v_pk_mul_f32 v[8:9], v[8:9], v[114:115] op_sel_hi:[1,0]
	v_pk_mul_f32 v[6:7], v[6:7], v[114:115] op_sel_hi:[1,0]
	v_pk_mul_f32 v[4:5], v[4:5], v[114:115] op_sel_hi:[1,0]
	v_pk_mul_f32 v[2:3], v[2:3], v[114:115] op_sel_hi:[1,0]
.LBB0_187:
	s_waitcnt lgkmcnt(0)
	s_barrier
	v_sub_f32_e32 v110, v49, v1
	v_sub_f32_e32 v111, v48, v1
	v_sub_f32_e32 v112, v47, v1
	v_sub_f32_e32 v113, v46, v1
	v_sub_f32_e32 v115, v45, v1
	v_sub_f32_e32 v116, v44, v1
	v_sub_f32_e32 v117, v43, v1
	v_sub_f32_e32 v118, v42, v1
	v_sub_f32_e32 v47, v41, v1
	v_sub_f32_e32 v46, v40, v1
	v_sub_f32_e32 v43, v39, v1
	v_sub_f32_e32 v42, v38, v1
	v_sub_f32_e32 v39, v37, v1
	v_sub_f32_e32 v38, v36, v1
	v_sub_f32_e32 v35, v35, v1
	v_sub_f32_e32 v34, v34, v1
	v_sub_f32_e32 v65, v65, v1
	v_sub_f32_e32 v64, v64, v1
	v_sub_f32_e32 v119, v63, v1
	v_sub_f32_e32 v62, v62, v1
	v_sub_f32_e32 v120, v61, v1
	v_sub_f32_e32 v60, v60, v1
	v_sub_f32_e32 v121, v59, v1
	v_sub_f32_e32 v58, v58, v1
	v_sub_f32_e32 v49, v57, v1
	v_sub_f32_e32 v48, v56, v1
	v_sub_f32_e32 v45, v55, v1
	v_sub_f32_e32 v44, v54, v1
	v_sub_f32_e32 v41, v53, v1
	v_sub_f32_e32 v40, v52, v1
	v_sub_f32_e32 v37, v51, v1
	v_sub_f32_e32 v36, v50, v1
	v_exp_f32_e32 v34, v34
	v_exp_f32_e32 v36, v36
	v_exp_f32_e32 v35, v35
	v_exp_f32_e32 v37, v37
	v_exp_f32_e32 v38, v38
	v_exp_f32_e32 v40, v40
	v_exp_f32_e32 v39, v39
	v_exp_f32_e32 v41, v41
	v_exp_f32_e32 v42, v42
	v_exp_f32_e32 v44, v44
	v_exp_f32_e32 v43, v43
	v_exp_f32_e32 v45, v45
	v_exp_f32_e32 v46, v46
	v_exp_f32_e32 v48, v48
	v_exp_f32_e32 v47, v47
	v_exp_f32_e32 v49, v49
	v_exp_f32_e32 v50, v118
	v_exp_f32_e32 v52, v58
	v_exp_f32_e32 v51, v117
	v_exp_f32_e32 v54, v116
	v_exp_f32_e32 v56, v60
	v_exp_f32_e32 v55, v115
	v_exp_f32_e32 v58, v113
	v_exp_f32_e32 v60, v62
	v_exp_f32_e32 v59, v112
	v_exp_f32_e32 v62, v111
	v_exp_f32_e32 v64, v64
	v_exp_f32_e32 v63, v110
	v_exp_f32_e32 v65, v65
	v_exp_f32_e32 v61, v119
	v_exp_f32_e32 v57, v120
	v_exp_f32_e32 v53, v121
	v_pk_add_f32 v[110:111], v[64:65], v[62:63]
	v_pk_add_f32 v[112:113], v[60:61], v[58:59]
	v_pk_add_f32 v[116:117], v[56:57], v[54:55]
	v_pk_add_f32 v[118:119], v[52:53], v[50:51]
	v_pk_add_f32 v[120:121], v[48:49], v[46:47]
	v_pk_add_f32 v[122:123], v[44:45], v[42:43]
	v_pk_add_f32 v[124:125], v[40:41], v[38:39]
	v_pk_add_f32 v[162:163], v[36:37], v[34:35]
	v_add_f32_e32 v124, v124, v125
	v_add_f32_e32 v115, v162, v163
	v_add_f32_e32 v122, v122, v123
	v_add_f32_e32 v120, v120, v121
	v_add_f32_e32 v118, v118, v119
	v_add_f32_e32 v116, v116, v117
	v_add_f32_e32 v112, v112, v113
	v_add_f32_e32 v110, v110, v111
	v_add_f32_e32 v115, v115, v124
	v_add_f32_e32 v120, v122, v120
	v_add_f32_e32 v116, v118, v116
	v_add_f32_e32 v110, v112, v110
	v_add_f32_e32 v111, v115, v120
	v_add_f32_e32 v110, v116, v110
	v_add_f32_e32 v162, v111, v110
	v_fmac_f32_e32 v162, v206, v114
	v_cvt_pk_bf16_f32 v122, v34, v35
	v_cvt_pk_bf16_f32 v123, v38, v39
	v_cvt_pk_bf16_f32 v124, v42, v43
	v_cvt_pk_bf16_f32 v125, v46, v47
	v_cvt_pk_bf16_f32 v118, v50, v51
	v_cvt_pk_bf16_f32 v119, v54, v55
	v_cvt_pk_bf16_f32 v120, v58, v59
	v_cvt_pk_bf16_f32 v121, v62, v63
	v_cvt_pk_bf16_f32 v114, v36, v37
	v_cvt_pk_bf16_f32 v115, v40, v41
	v_cvt_pk_bf16_f32 v116, v44, v45
	v_cvt_pk_bf16_f32 v117, v48, v49
	v_cvt_pk_bf16_f32 v110, v52, v53
	v_cvt_pk_bf16_f32 v111, v56, v57
	v_cvt_pk_bf16_f32 v112, v60, v61
	v_cvt_pk_bf16_f32 v113, v64, v65
	v_mov_b32_e32 v206, v162
	s_branch .LBB0_189
.LBB0_188:
	s_barrier
	v_mov_b32_e32 v1, v207
.LBB0_189:
	s_add_i32 s37, s47, -1
	s_sub_i32 s50, s50, 64
	s_addk_i32 s49, 0xc000
	s_cmp_lt_i32 s47, 1
	v_add_u32_e32 v175, 0xffffff00, v175
	s_cbranch_scc1 .LBB0_171
	s_waitcnt lgkmcnt(0)
	s_mov_b32 s47, s37
	v_mov_b32_e32 v207, v1
	s_cmp_lt_u32 s47, 2
	s_mov_b64 s[38:39], -1
	s_cbranch_scc1 .LBB0_175
	s_branch .LBB0_176
